# odd-layer mixer phase: waves 0-3 start the S5 scan immediately while waves 4-7 do the whole retention rotary pass (was: all waves rotary, then waves 4-7 idle during S5)
# speedup vs baseline: 1.0146x; 1.0016x over previous
; __global__ void __launch_bounds__(512, 2) mega_fwd(Params P) {
;     ...
;                     { PHASE_IDS();
;                     for (size_t idx0 = gtid; idx0 < (size_t)T_TOK * 32; idx0 += GT * 4) {
;                         u32x4 av[4], bv4[4]; f32x4 tv[4][4];
; #pragma unroll
;                         for (int q = 0; q < 4; ++q) { const size_t idx = idx0 + (size_t)q * GT; const bool ok = idx < (size_t)T_TOK * 32; const size_t ix = ok ? idx : 0;
;                             const int row = (int)(ix >> 5), sub = (int)(ix & 31), qk = sub >> 4, h = (sub >> 2) & 3, c = sub & 3, pos = row & (SEQ - 1);
;                             const bf16_t* p = Z + (size_t)row * ZW + 512 + qk * 256 + h * 64 + c * 8; av[q] = *(const u32x4*)p; bv4[q] = *(const u32x4*)(p + 32);
;     ...
;                     if (wave < 4) {
.LBB0_714:
	s_or_b64 exec, exec, s[2:3]
	v_readlane_b32 s4, v255, 32
	v_readlane_b32 s5, v255, 33
	s_mov_b64 s[2:3], -1
	s_and_b64 vcc, exec, s[4:5]
	s_waitcnt lgkmcnt(0)
	s_barrier
	s_cbranch_vccz .LBB0_867
	v_readfirstlane_b32 s1, v211
	s_lshr_b32 s1, s1, 6
	s_cmp_lt_u32 s1, 4
	s_cbranch_scc1 .Lmy_s5_entry
	v_readlane_b32 s1, v254, 0
	v_readlane_b32 s2, v254, 7
	s_and_b32 s4, s1, 1
	s_lshl_b32 s4, s4, 8
	s_sub_u32 s4, s4, 0x100
	v_add_u32_e32 v2, s4, v211
	s_lshr_b32 s2, s2, 1
	s_lshr_b32 s4, s1, 1
	s_ashr_i32 s5, s4, 31
	s_lshl_b64 s[6:7], s[4:5], 9
	v_ashrrev_i32_e32 v3, 31, v2
	v_readlane_b32 s8, v254, 3
	v_lshl_add_u64 v[74:75], s[6:7], 0, v[2:3]
	v_readlane_b32 s10, v254, 5
	v_readlane_b32 s11, v254, 6
	s_mov_b64 s[28:29], 0x200000
	v_readlane_b32 s9, v254, 4
	s_mov_b64 s[6:7], s[10:11]
	v_readlane_b32 s1, v255, 35
	v_cmp_gt_u64_e32 vcc, s[28:29], v[74:75]
	v_readlane_b32 s3, v254, 8
	s_and_saveexec_b64 s[8:9], vcc
	s_cbranch_execz .LBB0_724
	s_ashr_i32 s3, s2, 31
	s_lshl_b64 s[10:11], s[2:3], 9
	s_add_u32 s12, s6, 0x120000
	s_addc_u32 s13, s7, 0
	s_add_u32 s14, s6, 0x15800000
	s_addc_u32 s15, s7, 0
	s_lshl_b64 s[6:7], s[4:5], 13
	s_lshl_b64 s[4:5], s[4:5], 12
	s_lshl_b64 s[16:17], s[2:3], 11
	v_lshl_add_u64 v[76:77], v[2:3], 4, s[6:7]
	s_lshl_b64 s[18:19], s[2:3], 15
	v_lshl_add_u64 v[78:79], v[2:3], 3, s[4:5]
	s_lshl_b64 s[20:21], s[2:3], 14
	s_lshl_b64 s[22:23], s[2:3], 10
	s_mul_hi_i32 s25, s2, 0x600
	s_mul_i32 s24, s2, 0x600
	s_mov_b64 s[26:27], 0
	s_branch .LBB0_718

; __device__ __forceinline__ void s5_unit(LAS unsigned char* lw, int b, int g, const float* lam_re, const float* lam_im, const float* log_step, ...
;     const int n = lane, r = lane & 15, g4 = lane >> 4;
;     LAS float* U = (LAS float*)lw; LAS bf16_t* H = (LAS bf16_t*)(lw + 2048); LAS float* Xs = (LAS float*)(lw + 2048 + 8704); LAS f32x2* Fs = (LAS f32x2*)(lw + 2048 + 8704 + 16896);
;     const float step = expf(log_step[g]); const float lr = fminf(lam_re[g * 64 + n], -1e-4f), li = lam_im[g * 64 + n];
;     const float mag = expf(lr * step); float sn, cs; sincos_acc(li * step, sn, cs);
;     const float are = mag * cs, aim = mag * sn;
;     { const float den = lr * lr + li * li, nr = are - 1.0f, ni = aim; Fs[n] = (f32x2){(nr * lr + ni * li) / den, (ni * lr - nr * li) / den}; }
;     WSYNC();
;     bf16x8 Bf[8];
; #pragma unroll
;     for (int nb = 0; nb < 8; ++nb) {
;         const int ns = (nb & 3) * 16 + r; const f32x2 f = Fs[ns];
;         u32x4 wv = (u32x4){0u, 0u, 0u, 0u};
;         if (g4 < 2) {
;             const f32x4 br0 = *(const f32x4*)(b_re + (size_t)(g * 64 + ns) * 16 + g4 * 8), br1 = *(const f32x4*)(b_re + (size_t)(g * 64 + ns) * 16 + g4 * 8 + 4);
;             const f32x4 bi0 = *(const f32x4*)(b_im + (size_t)(g * 64 + ns) * 16 + g4 * 8), bi1 = *(const f32x4*)(b_im + (size_t)(g * 64 + ns) * 16 + g4 * 8 + 4);
;             f32x4 v0, v1;
;             if (nb < 4) { v0 = br0 * f.x - bi0 * f.y; v1 = br1 * f.x - bi1 * f.y; } else { v0 = bi0 * f.x + br0 * f.y; v1 = bi1 * f.x + br1 * f.y; }
;             wv.x = cvt_pk_bf16(v0[0], v0[1]); wv.y = cvt_pk_bf16(v0[2], v0[3]); wv.z = cvt_pk_bf16(v1[0], v1[1]); wv.w = cvt_pk_bf16(v1[2], v1[3]);
;         }
;         Bf[nb] = __builtin_bit_cast(bf16x8, wv);
;     }
;     bf16x8 CfT[4];
; #pragma unroll
;     for (int kk = 0; kk < 4; ++kk)
; #pragma unroll
;         for (int e = 0; e < 8; ++e) { const int kf_ = kk * 32 + g4 * 8 + e, n_ = kf_ >> 1;
;             const float v = (kf_ & 1) ? -c_im[(size_t)(g * 16 + r) * 64 + n_] : c_re[(size_t)(g * 16 + r) * 64 + n_];
; __global__ void __launch_bounds__(512, 2) mega_fwd(Params P) {
;     ...
;                     if (wave < 4) {
;                         for (int u = blk * 4 + wave; u < 1024; u += G * 4)
;                             s5_unit(lds + wave * S5_LDS_WAVE, u >> 5, u & 31, P.in[21] + (size_t)hl * 2048, P.in[22] + (size_t)hl * 2048, P.in[23] + (size_t)hl * 32,
.Lmy_s5_entry:
	v_readlane_b32 s4, v254, 7
	v_readlane_b32 s5, v254, 8
	s_mov_b32 s20, s4
	v_readlane_b32 s4, v254, 3
	v_mov_b32_e32 v2, v211
	v_readlane_b32 s6, v254, 5
	v_readlane_b32 s7, v254, 6
	s_waitcnt lgkmcnt(0)
	v_readlane_b32 s1, v254, 0
	v_readfirstlane_b32 s3, v2
	v_readlane_b32 s5, v254, 4
	s_mov_b64 s[18:19], s[6:7]
	s_ashr_i32 s2, s3, 6
	s_cmp_lt_i32 s2, 4
	v_readlane_b32 s4, v255, 35
	s_cbranch_scc0 .LBB0_747
	s_lshl_b32 s21, s1, 2
	s_add_i32 s1, s21, s2
	s_cmpk_gt_i32 s1, 0x3ff
	s_cbranch_scc1 .LBB0_747
	s_add_u32 s6, s18, 0x15800000
	s_addc_u32 s7, s19, 0
	s_add_u32 s22, s18, 0x33800000
	s_addc_u32 s23, s19, 0
	s_ashr_i32 s4, s4, 1
	s_mulk_i32 s2, 0x6e00
	s_ashr_i32 s5, s4, 31
	v_readlane_b32 s40, v254, 41
	s_lshr_b32 s28, s3, 6
	s_add_i32 s29, s2, 0
	s_lshl_b64 s[2:3], s[4:5], 11
	s_lshl_b64 s[10:11], s[4:5], 13
	v_readlane_b32 s50, v254, 51
	v_readlane_b32 s51, v254, 52
	s_add_u32 s8, s50, s10
	v_readlane_b32 s52, v254, 53
	s_addc_u32 s9, s51, s11
	v_readlane_b32 s53, v254, 54
	s_add_u32 s10, s52, s10
	v_readlane_b32 s54, v254, 55
	s_addc_u32 s11, s53, s11
	s_lshl_b64 s[12:13], s[4:5], 7
	v_readlane_b32 s41, v254, 42
	v_readlane_b32 s42, v254, 43
	v_readlane_b32 s43, v254, 44
	v_readlane_b32 s44, v254, 45
	v_readlane_b32 s45, v254, 46
	v_readlane_b32 s46, v254, 47
	v_readlane_b32 s47, v254, 48
	v_readlane_b32 s48, v254, 49
	v_readlane_b32 s49, v254, 50
	v_readlane_b32 s55, v254, 56
	s_add_u32 s12, s54, s12
	s_addc_u32 s13, s55, s13
	s_lshl_b64 s[4:5], s[4:5], 17
	v_readlane_b32 s40, v254, 57
	v_readlane_b32 s41, v254, 58
	s_add_u32 s24, s40, s4
	v_readlane_b32 s42, v254, 59
	s_addc_u32 s25, s41, s5
	v_readlane_b32 s43, v254, 60
	s_add_u32 s26, s42, s4
	v_readlane_b32 s44, v254, 61
	s_addc_u32 s27, s43, s5
	v_readlane_b32 s45, v254, 62
	s_add_u32 s14, s44, s4
	v_readlane_b32 s46, v254, 63
	s_addc_u32 s15, s45, s5
	v_readlane_b32 s47, v255, 0
	s_add_u32 s16, s46, s4
	v_readlane_b32 s48, v255, 1
	s_addc_u32 s17, s47, s5
	v_bfe_u32 v3, v2, 4, 2
	v_readlane_b32 s49, v255, 2
	s_add_u32 s4, s48, s2
	v_lshlrev_b32_e32 v0, 5, v3
	v_and_b32_e32 v67, 63, v2
	s_addc_u32 s5, s49, s3
	v_and_b32_e32 v134, 15, v2
	v_lshlrev_b32_e32 v66, 3, v3
	v_lshl_add_u64 v[68:69], s[24:25], 0, v[0:1]
	v_lshl_add_u64 v[70:71], s[26:27], 0, v[0:1]
	v_and_b32_e32 v0, 48, v2
	v_lshlrev_b32_e32 v5, 3, v67
	v_lshl_add_u64 v[72:73], s[4:5], 0, v[0:1]
	v_add_u32_e32 v143, s29, v0
	s_lshl_b32 s24, s20, 2
	s_add_i32 s25, s21, s28
	v_lshl_or_b32 v0, v134, 10, v66
	v_bfe_u32 v7, v2, 1, 5
	v_and_b32_e32 v8, 8, v5
	v_lshl_add_u64 v[74:75], s[18:19], 0, v[0:1]
	s_add_u32 s18, s18, 0x15828000
	v_readlane_b32 s50, v255, 3
	v_readlane_b32 s51, v255, 4
	v_readlane_b32 s52, v255, 5
	v_readlane_b32 s53, v255, 6
	v_readlane_b32 s54, v255, 7
	v_readlane_b32 s55, v255, 8
	v_add_u32_e32 v135, s29, v5
	v_or_b32_e32 v139, 48, v67
	v_lshlrev_b32_e32 v141, 6, v134
	v_lshlrev_b32_e32 v4, 2, v3
	v_lshlrev_b32_e32 v3, 6, v7
	v_lshlrev_b32_e32 v5, 2, v8
	v_mov_b64_e32 v[14:15], s[6:7]
	s_addc_u32 s19, s19, 0
	v_mul_u32_u24_e32 v0, 0x1400, v7
	v_and_b32_e32 v2, 1, v2
	v_mul_u32_u24_e32 v6, 0xa00, v7
	v_mul_u32_u24_e32 v10, 0xa00, v134
	v_add3_u32 v142, s29, v3, v5
	v_mul_u32_u24_e32 v5, 0x210, v134
	v_mul_u32_u24_e32 v9, 0x110, v134
	v_lshlrev_b32_e32 v12, 9, v134
	v_or_b32_e32 v11, v141, v4
	v_mad_u64_u32 v[76:77], s[20:21], v139, s57, v[14:15]
	v_mov_b64_e32 v[14:15], s[18:19]
	v_mul_hi_u32_u24_e32 v3, 0x1400, v7
	v_lshl_or_b32 v2, v2, 4, v0
	s_mov_b32 s30, 0x6dc9c883
	s_mov_b32 s36, 0x54442d18
	s_mov_b32 s40, 0x55555555
	s_mov_b32 s42, 0x9999999a
	s_mov_b32 s44, 0x11111111
	s_mov_b32 s46, 0x18618618
	s_mov_b32 s48, 0x92492492
	s_mov_b32 s50, 0x1c71c71c
	s_mov_b32 s52, 0x16c16c17
	s_mov_b32 s54, 0x29e4129e
	v_cmp_gt_u32_e64 s[2:3], 32, v67
	v_lshl_add_u32 v136, v134, 3, s29
	v_or_b32_e32 v137, 16, v134
	v_or_b32_e32 v138, 32, v134
	v_lshl_add_u32 v140, v139, 3, s29
	v_cmp_lt_u32_e64 s[4:5], 31, v67
	v_lshl_add_u32 v144, v67, 2, s29
	v_mad_u64_u32 v[78:79], s[20:21], v134, s57, v[14:15]
	v_lshl_add_u64 v[80:81], s[18:19], 0, v[2:3]
	v_lshlrev_b32_e32 v145, 2, v11
	v_lshlrev_b32_e32 v0, 1, v6
	v_lshlrev_b32_e32 v82, 1, v8
	v_lshlrev_b32_e32 v84, 1, v10
	v_lshlrev_b32_e32 v86, 1, v4
	v_lshlrev_b32_e32 v88, 1, v12
	v_add_u32_e32 v146, v143, v5
	v_add_u32_e32 v147, v143, v9
	s_mov_b32 s31, 0x3fc45f30
	s_mov_b32 s37, 0xc01921fb
	s_mov_b32 s41, 0x3fc55555
	s_mov_b32 s43, 0x3fa99999
	s_mov_b32 s45, 0x3fa11111
	s_mov_b32 s47, 0x3f986186
	s_mov_b32 s49, 0x3f924924
	s_mov_b32 s51, 0x3f8c71c7
	s_mov_b32 s53, 0x3f86c16c
	s_mov_b32 s55, 0x3f829e41
